# phase 0 weight transposes: non-temporal loads of the once-read f32 weights and non-temporal stores of the bf16 copies
# speedup vs baseline: 1.0135x; 1.0135x over previous
.LBB0_20:
	v_add_u32_e32 v2, 0xc200, v41
	v_add_u32_e32 v4, 0xc400, v41
	v_add_u32_e32 v6, 0xc600, v41
	ds_read2_b32 v[2:3], v2 offset0:64 offset1:129
	ds_read2_b32 v[4:5], v4 offset0:66 offset1:131
	ds_read2_b32 v[6:7], v6 offset0:68 offset1:133
	s_waitcnt lgkmcnt(2)
	v_cvt_pk_bf16_f32 v2, v2, v3
	s_waitcnt lgkmcnt(1)
	v_cvt_pk_bf16_f32 v3, v4, v5
	s_waitcnt lgkmcnt(0)
	v_cvt_pk_bf16_f32 v4, v6, v7
	v_add_u32_e32 v6, s24, v31
	v_mul_hi_u32_u24_e32 v7, s16, v6
	v_mul_u32_u24_e32 v6, s16, v6
	v_lshl_add_u64 v[6:7], v[6:7], 1, s[14:15]
	v_lshl_add_u64 v[6:7], s[2:3], 1, v[6:7]
	s_add_i32 s34, s34, s43
	s_add_i32 s44, s44, s45
	s_add_i32 s46, s46, s47
	s_add_i32 s48, s48, s49
	v_add_u32_e32 v8, 0xc800, v41
	v_lshl_add_u64 v[6:7], v[6:7], 0, v[26:27]
	s_cmpk_gt_i32 s34, 0x27ff
	ds_read2_b32 v[8:9], v8 offset0:70 offset1:135
	s_waitcnt lgkmcnt(0)
	v_cvt_pk_bf16_f32 v5, v8, v9
	global_store_dwordx4 v[6:7], v[2:5], off nt
	s_barrier
	s_cbranch_scc1 .LBB0_149

.LBB0_101:
	ds_read2_b32 v[2:3], v41 offset1:65
	ds_read2_b32 v[4:5], v41 offset0:130 offset1:195
	v_add_u32_e32 v8, 0x400, v41
	ds_read2_b32 v[6:7], v8 offset0:4 offset1:69
	ds_read2_b32 v[8:9], v8 offset0:134 offset1:199
	s_andn2_b64 vcc, exec, s[18:19]
	s_waitcnt lgkmcnt(3)
	v_cvt_pk_bf16_f32 v2, v2, v3
	s_waitcnt lgkmcnt(2)
	v_cvt_pk_bf16_f32 v3, v4, v5
	s_waitcnt lgkmcnt(1)
	v_cvt_pk_bf16_f32 v4, v6, v7
	v_or_b32_e32 v6, s50, v31
	v_mul_hi_u32_u24_e32 v7, s28, v6
	v_mul_u32_u24_e32 v6, s28, v6
	v_lshl_add_u64 v[6:7], v[6:7], 1, s[26:27]
	v_lshl_add_u64 v[6:7], s[2:3], 1, v[6:7]
	v_lshl_add_u64 v[6:7], v[6:7], 0, v[26:27]
	s_mov_b64 s[26:27], -1
	s_waitcnt lgkmcnt(0)
	v_cvt_pk_bf16_f32 v5, v8, v9
	global_store_dwordx4 v[6:7], v[2:5], off nt
	s_cbranch_vccnz .LBB0_115
	s_cmpk_lt_u32 s34, 0x600
	s_cbranch_scc1 .LBB0_112
	s_cmpk_lt_u32 s34, 0x800
	s_cbranch_scc1 .LBB0_109
	s_cmpk_lt_u32 s34, 0x1800
	s_mov_b64 s[24:25], -1
	s_cbranch_scc1 .LBB0_106
	s_add_i32 s2, s34, 0xffffe801
	s_lshr_b32 s2, s2, 10
	s_add_i32 s18, s48, 64
	s_and_b32 s26, s44, 0xfc0
	s_and_b32 s28, s18, 0x340
	s_lshl_b64 s[18:19], s[2:3], 23
	s_add_u32 s18, s35, s18
	s_addc_u32 s19, s36, s19
	s_mov_b64 s[24:25], 0
	s_mov_b32 s2, s26

.LBB0_117:
	v_add_u32_e32 v2, 0x4000, v41
	v_add_u32_e32 v4, 0x4200, v41
	v_add_u32_e32 v6, 0x4400, v41
	ds_read2_b32 v[2:3], v2 offset0:64 offset1:129
	ds_read2_b32 v[4:5], v4 offset0:66 offset1:131
	ds_read2_b32 v[6:7], v6 offset0:68 offset1:133
	s_waitcnt lgkmcnt(2)
	v_cvt_pk_bf16_f32 v2, v2, v3
	s_waitcnt lgkmcnt(1)
	v_cvt_pk_bf16_f32 v3, v4, v5
	s_waitcnt lgkmcnt(0)
	v_cvt_pk_bf16_f32 v4, v6, v7
	v_add_u32_e32 v6, s28, v31
	v_mul_hi_u32_u24_e32 v7, s24, v6
	v_mul_u32_u24_e32 v6, s24, v6
	v_lshl_add_u64 v[6:7], v[6:7], 1, s[18:19]
	v_lshl_add_u64 v[6:7], s[2:3], 1, v[6:7]
	v_add_u32_e32 v8, 0x4600, v41
	v_lshl_add_u64 v[6:7], v[6:7], 0, v[26:27]
	s_andn2_b64 vcc, exec, s[16:17]
	s_mov_b64 s[24:25], -1
	ds_read2_b32 v[8:9], v8 offset0:70 offset1:135
	s_waitcnt lgkmcnt(0)
	v_cvt_pk_bf16_f32 v5, v8, v9
	global_store_dwordx4 v[6:7], v[2:5], off nt
	s_cbranch_vccnz .LBB0_131
	s_cmpk_lt_u32 s34, 0x600
	s_cbranch_scc1 .LBB0_128
	s_cmpk_lt_u32 s34, 0x800
	s_cbranch_scc1 .LBB0_125
	s_cmpk_lt_u32 s34, 0x1800
	s_mov_b64 s[18:19], -1
	s_cbranch_scc1 .LBB0_122
	s_add_i32 s2, s34, 0xffffe802
	s_lshr_b32 s2, s2, 10
	s_add_i32 s16, s48, 0x80
	s_and_b32 s24, s44, 0xfc0
	s_and_b32 s26, s16, 0x380
	s_lshl_b64 s[16:17], s[2:3], 23
	s_add_u32 s16, s35, s16
	s_addc_u32 s17, s36, s17
	s_mov_b64 s[18:19], 0
	s_mov_b32 s2, s24

.LBB0_133:
	v_add_u32_e32 v2, 0x8000, v41
	v_add_u32_e32 v6, 0x8400, v41
	ds_read2_b32 v[2:3], v2 offset0:128 offset1:193
	ds_read2_b32 v[4:5], v6 offset0:2 offset1:67
	ds_read2_b32 v[6:7], v6 offset0:132 offset1:197
	s_waitcnt lgkmcnt(2)
	v_cvt_pk_bf16_f32 v2, v2, v3
	s_waitcnt lgkmcnt(1)
	v_cvt_pk_bf16_f32 v3, v4, v5
	s_waitcnt lgkmcnt(0)
	v_cvt_pk_bf16_f32 v4, v6, v7
	v_or_b32_e32 v6, s26, v31
	v_mul_hi_u32_u24_e32 v7, s18, v6
	v_mul_u32_u24_e32 v6, s18, v6
	v_lshl_add_u64 v[6:7], v[6:7], 1, s[16:17]
	v_lshl_add_u64 v[6:7], s[2:3], 1, v[6:7]
	v_add_u32_e32 v8, 0x8800, v41
	v_lshl_add_u64 v[6:7], v[6:7], 0, v[26:27]
	s_andn2_b64 vcc, exec, s[14:15]
	s_mov_b64 s[18:19], -1
	ds_read2_b32 v[8:9], v8 offset0:6 offset1:71
	s_waitcnt lgkmcnt(0)
	v_cvt_pk_bf16_f32 v5, v8, v9
	global_store_dwordx4 v[6:7], v[2:5], off nt
	s_cbranch_vccnz .LBB0_147
	s_cmpk_lt_u32 s34, 0x600
	s_cbranch_scc1 .LBB0_144
	s_cmpk_lt_u32 s34, 0x800
	s_cbranch_scc1 .LBB0_141
	s_cmpk_lt_u32 s34, 0x1800
	s_mov_b64 s[16:17], -1
	s_cbranch_scc1 .LBB0_138
	s_add_i32 s2, s34, 0xffffe803
	s_lshr_b32 s2, s2, 10
	s_add_i32 s14, s48, 0xc0
	s_and_b32 s18, s44, 0xfc0
	s_and_b32 s24, s14, 0x3c0
	s_lshl_b64 s[14:15], s[2:3], 23
	s_add_u32 s14, s35, s14
	s_addc_u32 s15, s36, s15
	s_mov_b64 s[16:17], 0
	s_mov_b32 s2, s18
